# v9 stack plus per-layer L1 invalidate issued at the end of the previous layer's GEMM2 tile
# baseline (speedup 1.0000x reference)
.LBB0_474:
	v_readfirstlane_b32 s100, v218
	s_nop 3
	s_cmp_lt_u32 s100, 64
	s_cbranch_scc0 .Lg2_noinv
	buffer_inv sc1

.LBB0_536:
	s_waitcnt vmcnt(0) lgkmcnt(0)
	s_waitcnt vmcnt(0)
